# v51 + gate/up epilogue: store addresses of row groups 1..7 from group 0's address + scalar constant
# speedup vs baseline: 1.0001x; 1.0001x over previous
; __device__ __forceinline__ unsigned pk_bf16(float lo, float hi) { f32x2 v = {lo, hi}; bf16x2_t b = __builtin_convertvector(v, bf16x2_t); return __builtin_bit_cast(unsigned, b); }
;     __device__ __forceinline__ void operator()(const f32x4 (&acc)[2][2][4][2], const Unit& u, int wr, int wc, int fr, int fq) const {
;     ...
; #pragma unroll
;         for (int ai = 0; ai < 2; ++ai)
; #pragma unroll
;             for (int m = 0; m < 4; ++m) {
;                 float o[8]; const float rv = rsqrtf(rowss[row0 + ai * HALF + m * 16] * (1.0f / 1024.0f) + 1e-6f);
; #pragma unroll
;                 for (int n = 0; n < 2; ++n)
; #pragma unroll
;                     for (int j = 0; j < 4; ++j) { const float g = acc[ai][0][m][n][j] * rv + bz[0][n][j], up = acc[ai][1][m][n][j] * rv + bz[1][n][j];
;                         o[4 * n + j] = g * __builtin_amdgcn_rcpf(1.0f + __expf(-g)) * up; }
;                 u32x4 w; w.x = pk_bf16(o[0], o[1]); w.y = pk_bf16(o[2], o[3]); w.z = pk_bf16(o[4], o[5]); w.w = pk_bf16(o[6], o[7]);
;                 *(u32x4*)(act + (size_t)(row0 + ai * HALF + m * 16) * 2816 + col0) = w;
;             }
.LBB0_907:
	s_ashr_i32 s4, s34, 6
	s_mul_hi_i32 s5, s4, 0x5800
	s_mulk_i32 s4, 0x5800
	v_lshl_add_u32 v156, s34, 8, v162
	s_add_u32 s34, s14, s4
	s_addc_u32 s37, s15, s5
	s_lshl_b32 s4, s31, 8
	s_ashr_i32 s5, s4, 31
	s_lshl_b64 s[4:5], s[4:5], 2
	s_add_u32 s4, s34, s4
	s_addc_u32 s5, s37, s5
	s_add_u32 s4, s4, s30
	v_ashrrev_i32_e32 v157, 31, v156
	s_addc_u32 s5, s5, 0
	v_lshl_add_u64 v[158:159], v[156:157], 2, s[42:43]
	v_lshl_or_b32 v160, s31, 7, v164
	v_ashrrev_i32_e32 v161, 31, v160
	s_movk_i32 s12, 0x1600
	s_mov_b64 s[54:55], -1
	s_waitcnt vmcnt(8)
	v_fmamk_f32 v157, v147, 0x3a800000, v227
	s_nop 0
	v_rsq_f32_e32 v157, v157
	s_nop 0
	v_mov_b32_e32 v168, v157
	v_pk_fma_f32 v[142:143], v[142:143], v[168:169], v[246:247] op_sel_hi:[1,0,1]
	v_pk_fma_f32 v[134:135], v[134:135], v[168:169], v[238:239] op_sel_hi:[1,0,1]
	v_mul_f32_e32 v157, 0xbfb8aa3b, v142
	v_exp_f32_e32 v157, v157
	v_pk_fma_f32 v[136:137], v[136:137], v[168:169], v[240:241] op_sel_hi:[1,0,1]
	v_pk_fma_f32 v[138:139], v[138:139], v[168:169], v[242:243] op_sel_hi:[1,0,1]
	v_pk_fma_f32 v[130:131], v[130:131], v[168:169], v[174:175] op_sel_hi:[1,0,1]
	v_add_f32_e32 v157, 1.0, v157
	v_rcp_f32_e32 v170, v157
	v_mul_f32_e32 v157, 0xbfb8aa3b, v143
	v_exp_f32_e32 v157, v157
	v_pk_fma_f32 v[132:133], v[132:133], v[168:169], v[176:177] op_sel_hi:[1,0,1]
	v_add_f32_e32 v157, 1.0, v157
	v_rcp_f32_e32 v171, v157
	s_nop 0
	v_pk_mul_f32 v[142:143], v[142:143], v[170:171]
	s_nop 0
	v_pk_mul_f32 v[134:135], v[134:135], v[142:143]
	v_pk_fma_f32 v[142:143], v[144:145], v[168:169], v[248:249] op_sel_hi:[1,0,1]
	s_nop 0
	v_mul_f32_e32 v144, 0xbfb8aa3b, v142
	v_mul_f32_e32 v145, 0xbfb8aa3b, v143
	v_exp_f32_e32 v144, v144
	v_exp_f32_e32 v145, v145
	v_add_f32_e32 v144, 1.0, v144
	v_add_f32_e32 v145, 1.0, v145
	v_rcp_f32_e32 v144, v144
	v_rcp_f32_e32 v145, v145
	s_nop 0
	v_pk_mul_f32 v[142:143], v[142:143], v[144:145]
	s_nop 0
	v_pk_mul_f32 v[136:137], v[136:137], v[142:143]
	v_mul_f32_e32 v142, 0xbfb8aa3b, v138
	v_mul_f32_e32 v143, 0xbfb8aa3b, v139
	v_exp_f32_e32 v142, v142
	v_exp_f32_e32 v143, v143
	v_add_f32_e32 v142, 1.0, v142
	v_add_f32_e32 v143, 1.0, v143
	v_rcp_f32_e32 v142, v142
	v_rcp_f32_e32 v143, v143
	s_nop 0
	v_pk_mul_f32 v[138:139], v[138:139], v[142:143]
	s_nop 0
	v_pk_mul_f32 v[138:139], v[130:131], v[138:139]
	v_pk_fma_f32 v[130:131], v[140:141], v[168:169], v[244:245] op_sel_hi:[1,0,1]
	s_nop 0
	v_mul_f32_e32 v140, 0xbfb8aa3b, v130
	v_mul_f32_e32 v141, 0xbfb8aa3b, v131
	v_exp_f32_e32 v140, v140
	v_exp_f32_e32 v141, v141
	v_add_f32_e32 v140, 1.0, v140
	v_add_f32_e32 v141, 1.0, v141
	v_rcp_f32_e32 v140, v140
	v_rcp_f32_e32 v141, v141
	s_nop 0
	v_pk_mul_f32 v[130:131], v[130:131], v[140:141]
	s_nop 0
	v_pk_mul_f32 v[140:141], v[132:133], v[130:131]
	v_cvt_pk_bf16_f32 v130, v134, v135
	v_mov_b64_e32 v[134:135], s[2:3]
	v_cvt_pk_bf16_f32 v131, v136, v137
	v_cvt_pk_bf16_f32 v132, v138, v139
	v_mad_i64_i32 v[138:139], s[4:5], v156, s12, v[134:135]
	v_lshlrev_b64 v[136:137], 1, v[160:161]
	v_cvt_pk_bf16_f32 v133, v140, v141
	s_mov_b32 s99, 0
	v_lshl_add_u64 v[194:195], v[138:139], 0, v[136:137]
	global_store_dwordx4 v[194:195], v[130:133], off
	s_nop 1
	v_fmamk_f32 v131, v149, 0x3a800000, v227
	s_nop 0
	v_rsq_f32_e32 v131, v131
	s_nop 0
	v_mov_b32_e32 v132, v131
	v_pk_fma_f32 v[124:125], v[124:125], v[132:133], v[246:247] op_sel_hi:[1,0,1]
	v_pk_fma_f32 v[116:117], v[116:117], v[132:133], v[238:239] op_sel_hi:[1,0,1]
	v_mul_f32_e32 v131, 0xbfb8aa3b, v124
	v_exp_f32_e32 v131, v131
	v_pk_fma_f32 v[118:119], v[118:119], v[132:133], v[240:241] op_sel_hi:[1,0,1]
	v_pk_fma_f32 v[120:121], v[120:121], v[132:133], v[242:243] op_sel_hi:[1,0,1]
	v_pk_fma_f32 v[112:113], v[112:113], v[132:133], v[174:175] op_sel_hi:[1,0,1]
	v_add_f32_e32 v131, 1.0, v131
	v_rcp_f32_e32 v138, v131
	v_mul_f32_e32 v131, 0xbfb8aa3b, v125
	v_exp_f32_e32 v131, v131
	v_pk_fma_f32 v[114:115], v[114:115], v[132:133], v[176:177] op_sel_hi:[1,0,1]
	v_add_f32_e32 v131, 1.0, v131
	v_rcp_f32_e32 v139, v131
	s_nop 0
	v_pk_mul_f32 v[124:125], v[124:125], v[138:139]
	s_nop 0
	v_pk_mul_f32 v[116:117], v[116:117], v[124:125]
	v_pk_fma_f32 v[124:125], v[126:127], v[132:133], v[248:249] op_sel_hi:[1,0,1]
	s_nop 0
	v_mul_f32_e32 v126, 0xbfb8aa3b, v124
	v_mul_f32_e32 v127, 0xbfb8aa3b, v125
	v_exp_f32_e32 v126, v126
	v_exp_f32_e32 v127, v127
	v_add_f32_e32 v126, 1.0, v126
	v_add_f32_e32 v127, 1.0, v127
	v_rcp_f32_e32 v126, v126
	v_rcp_f32_e32 v127, v127
	s_nop 0
	v_pk_mul_f32 v[124:125], v[124:125], v[126:127]
	s_nop 0
	v_pk_mul_f32 v[118:119], v[118:119], v[124:125]
	v_mul_f32_e32 v124, 0xbfb8aa3b, v120
	v_mul_f32_e32 v125, 0xbfb8aa3b, v121
	v_exp_f32_e32 v124, v124
	v_exp_f32_e32 v125, v125
	v_add_f32_e32 v124, 1.0, v124
	v_add_f32_e32 v125, 1.0, v125
	v_rcp_f32_e32 v124, v124
	v_rcp_f32_e32 v125, v125
	s_nop 0
	v_pk_mul_f32 v[120:121], v[120:121], v[124:125]
	s_nop 0
	v_pk_mul_f32 v[120:121], v[112:113], v[120:121]
	v_pk_fma_f32 v[112:113], v[122:123], v[132:133], v[244:245] op_sel_hi:[1,0,1]
	s_nop 0
	v_mul_f32_e32 v122, 0xbfb8aa3b, v112
	v_mul_f32_e32 v123, 0xbfb8aa3b, v113
	v_exp_f32_e32 v122, v122
	v_exp_f32_e32 v123, v123
	v_add_f32_e32 v122, 1.0, v122
	v_add_f32_e32 v123, 1.0, v123
	v_rcp_f32_e32 v122, v122
	v_rcp_f32_e32 v123, v123
	s_nop 0
	v_pk_mul_f32 v[112:113], v[112:113], v[122:123]
	s_nop 0
	v_pk_mul_f32 v[122:123], v[114:115], v[112:113]
	v_cvt_pk_bf16_f32 v112, v116, v117
	s_mov_b32 s98, 0x16000
	v_cvt_pk_bf16_f32 v113, v118, v119
	v_cvt_pk_bf16_f32 v114, v120, v121
	v_cvt_pk_bf16_f32 v115, v122, v123
	v_lshl_add_u64 v[116:117], v[194:195], 0, s[98:99]
	global_store_dwordx4 v[116:117], v[112:115], off
	s_nop 1
; __device__ __forceinline__ unsigned pk_bf16(float lo, float hi) { f32x2 v = {lo, hi}; bf16x2_t b = __builtin_convertvector(v, bf16x2_t); return __builtin_bit_cast(unsigned, b); }
;     __device__ __forceinline__ void operator()(const f32x4 (&acc)[2][2][4][2], const Unit& u, int wr, int wc, int fr, int fq) const {
;     ...
; #pragma unroll
;         for (int ai = 0; ai < 2; ++ai)
; #pragma unroll
;             for (int m = 0; m < 4; ++m) {
;                 float o[8]; const float rv = rsqrtf(rowss[row0 + ai * HALF + m * 16] * (1.0f / 1024.0f) + 1e-6f);
; #pragma unroll
;                 for (int n = 0; n < 2; ++n)
; #pragma unroll
;                     for (int j = 0; j < 4; ++j) { const float g = acc[ai][0][m][n][j] * rv + bz[0][n][j], up = acc[ai][1][m][n][j] * rv + bz[1][n][j];
;                         o[4 * n + j] = g * __builtin_amdgcn_rcpf(1.0f + __expf(-g)) * up; }
;                 u32x4 w; w.x = pk_bf16(o[0], o[1]); w.y = pk_bf16(o[2], o[3]); w.z = pk_bf16(o[4], o[5]); w.w = pk_bf16(o[6], o[7]);
;                 *(u32x4*)(act + (size_t)(row0 + ai * HALF + m * 16) * 2816 + col0) = w;
;             }
	v_fmamk_f32 v113, v151, 0x3a800000, v227
	s_nop 0
	v_rsq_f32_e32 v113, v113
	s_nop 0
	v_mov_b32_e32 v114, v113
	v_pk_fma_f32 v[108:109], v[108:109], v[114:115], v[246:247] op_sel_hi:[1,0,1]
	v_pk_fma_f32 v[100:101], v[100:101], v[114:115], v[238:239] op_sel_hi:[1,0,1]
	v_mul_f32_e32 v113, 0xbfb8aa3b, v108
	v_exp_f32_e32 v113, v113
	v_pk_fma_f32 v[102:103], v[102:103], v[114:115], v[240:241] op_sel_hi:[1,0,1]
	v_pk_fma_f32 v[104:105], v[104:105], v[114:115], v[242:243] op_sel_hi:[1,0,1]
	v_pk_fma_f32 v[96:97], v[96:97], v[114:115], v[174:175] op_sel_hi:[1,0,1]
	v_add_f32_e32 v113, 1.0, v113
	v_rcp_f32_e32 v116, v113
	v_mul_f32_e32 v113, 0xbfb8aa3b, v109
	v_exp_f32_e32 v113, v113
	v_pk_fma_f32 v[98:99], v[98:99], v[114:115], v[176:177] op_sel_hi:[1,0,1]
	v_add_f32_e32 v113, 1.0, v113
	v_rcp_f32_e32 v117, v113
	s_nop 0
	v_pk_mul_f32 v[108:109], v[108:109], v[116:117]
	s_nop 0
	v_pk_mul_f32 v[100:101], v[100:101], v[108:109]
	v_pk_fma_f32 v[108:109], v[110:111], v[114:115], v[248:249] op_sel_hi:[1,0,1]
	s_nop 0
	v_mul_f32_e32 v110, 0xbfb8aa3b, v108
	v_mul_f32_e32 v111, 0xbfb8aa3b, v109
	v_exp_f32_e32 v110, v110
	v_exp_f32_e32 v111, v111
	v_add_f32_e32 v110, 1.0, v110
	v_add_f32_e32 v111, 1.0, v111
	v_rcp_f32_e32 v110, v110
	v_rcp_f32_e32 v111, v111
	s_nop 0
	v_pk_mul_f32 v[108:109], v[108:109], v[110:111]
	s_nop 0
	v_pk_mul_f32 v[102:103], v[102:103], v[108:109]
	v_mul_f32_e32 v108, 0xbfb8aa3b, v104
	v_mul_f32_e32 v109, 0xbfb8aa3b, v105
	v_exp_f32_e32 v108, v108
	v_exp_f32_e32 v109, v109
	v_add_f32_e32 v108, 1.0, v108
	v_add_f32_e32 v109, 1.0, v109
	v_rcp_f32_e32 v108, v108
	v_rcp_f32_e32 v109, v109
	s_nop 0
	v_pk_mul_f32 v[104:105], v[104:105], v[108:109]
	s_nop 0
	v_pk_mul_f32 v[104:105], v[96:97], v[104:105]
	v_pk_fma_f32 v[96:97], v[106:107], v[114:115], v[244:245] op_sel_hi:[1,0,1]
	s_nop 0
	v_mul_f32_e32 v106, 0xbfb8aa3b, v96
	v_mul_f32_e32 v107, 0xbfb8aa3b, v97
	v_exp_f32_e32 v106, v106
	v_exp_f32_e32 v107, v107
	v_add_f32_e32 v106, 1.0, v106
	v_add_f32_e32 v107, 1.0, v107
	v_rcp_f32_e32 v106, v106
	v_rcp_f32_e32 v107, v107
	s_nop 0
	v_pk_mul_f32 v[96:97], v[96:97], v[106:107]
	s_nop 0
	v_pk_mul_f32 v[106:107], v[98:99], v[96:97]
	v_cvt_pk_bf16_f32 v96, v100, v101
	s_mov_b32 s98, 0x2c000
	v_cvt_pk_bf16_f32 v97, v102, v103
	v_cvt_pk_bf16_f32 v98, v104, v105
	v_cvt_pk_bf16_f32 v99, v106, v107
	v_lshl_add_u64 v[100:101], v[194:195], 0, s[98:99]
	global_store_dwordx4 v[100:101], v[96:99], off
	s_nop 1
	v_fmamk_f32 v97, v153, 0x3a800000, v227
	s_nop 0
	v_rsq_f32_e32 v97, v97
	s_nop 0
	v_mov_b32_e32 v98, v97
	v_pk_fma_f32 v[92:93], v[92:93], v[98:99], v[246:247] op_sel_hi:[1,0,1]
	v_pk_fma_f32 v[84:85], v[84:85], v[98:99], v[238:239] op_sel_hi:[1,0,1]
	v_mul_f32_e32 v97, 0xbfb8aa3b, v92
	v_exp_f32_e32 v97, v97
	v_pk_fma_f32 v[86:87], v[86:87], v[98:99], v[240:241] op_sel_hi:[1,0,1]
	v_pk_fma_f32 v[88:89], v[88:89], v[98:99], v[242:243] op_sel_hi:[1,0,1]
	v_pk_fma_f32 v[80:81], v[80:81], v[98:99], v[174:175] op_sel_hi:[1,0,1]
	v_add_f32_e32 v97, 1.0, v97
	v_rcp_f32_e32 v100, v97
	v_mul_f32_e32 v97, 0xbfb8aa3b, v93
	v_exp_f32_e32 v97, v97
	v_pk_fma_f32 v[82:83], v[82:83], v[98:99], v[176:177] op_sel_hi:[1,0,1]
	v_add_f32_e32 v97, 1.0, v97
	v_rcp_f32_e32 v101, v97
	s_nop 0
	v_pk_mul_f32 v[92:93], v[92:93], v[100:101]
	s_nop 0
	v_pk_mul_f32 v[84:85], v[84:85], v[92:93]
	v_pk_fma_f32 v[92:93], v[94:95], v[98:99], v[248:249] op_sel_hi:[1,0,1]
	s_nop 0
	v_mul_f32_e32 v94, 0xbfb8aa3b, v92
	v_mul_f32_e32 v95, 0xbfb8aa3b, v93
	v_exp_f32_e32 v94, v94
	v_exp_f32_e32 v95, v95
	v_add_f32_e32 v94, 1.0, v94
	v_add_f32_e32 v95, 1.0, v95
	v_rcp_f32_e32 v94, v94
	v_rcp_f32_e32 v95, v95
	s_nop 0
	v_pk_mul_f32 v[92:93], v[92:93], v[94:95]
	s_nop 0
	v_pk_mul_f32 v[86:87], v[86:87], v[92:93]
	v_mul_f32_e32 v92, 0xbfb8aa3b, v88
	v_mul_f32_e32 v93, 0xbfb8aa3b, v89
	v_exp_f32_e32 v92, v92
	v_exp_f32_e32 v93, v93
	v_add_f32_e32 v92, 1.0, v92
	v_add_f32_e32 v93, 1.0, v93
	v_rcp_f32_e32 v92, v92
	v_rcp_f32_e32 v93, v93
	s_nop 0
	v_pk_mul_f32 v[88:89], v[88:89], v[92:93]
	s_nop 0
	v_pk_mul_f32 v[88:89], v[80:81], v[88:89]
	v_pk_fma_f32 v[80:81], v[90:91], v[98:99], v[244:245] op_sel_hi:[1,0,1]
	s_nop 0
	v_mul_f32_e32 v90, 0xbfb8aa3b, v80
	v_mul_f32_e32 v91, 0xbfb8aa3b, v81
	v_exp_f32_e32 v90, v90
	v_exp_f32_e32 v91, v91
	v_add_f32_e32 v90, 1.0, v90
	v_add_f32_e32 v91, 1.0, v91
	v_rcp_f32_e32 v90, v90
	v_rcp_f32_e32 v91, v91
	s_nop 0
	v_pk_mul_f32 v[80:81], v[80:81], v[90:91]
	s_nop 0
	v_pk_mul_f32 v[90:91], v[82:83], v[80:81]
	v_cvt_pk_bf16_f32 v80, v84, v85
	s_mov_b32 s98, 0x42000
	v_cvt_pk_bf16_f32 v81, v86, v87
	v_cvt_pk_bf16_f32 v82, v88, v89
	v_cvt_pk_bf16_f32 v83, v90, v91
	v_lshl_add_u64 v[84:85], v[194:195], 0, s[98:99]
	global_store_dwordx4 v[84:85], v[80:83], off
	s_nop 0
	s_nop 0
	v_fmamk_f32 v80, v155, 0x3a800000, v227
	s_nop 0
	v_rsq_f32_e32 v80, v80
	s_nop 0
	v_pk_fma_f32 v[76:77], v[76:77], v[80:81], v[246:247] op_sel_hi:[1,0,1]
	v_pk_fma_f32 v[68:69], v[68:69], v[80:81], v[238:239] op_sel_hi:[1,0,1]
	v_mul_f32_e32 v82, 0xbfb8aa3b, v76
	v_mul_f32_e32 v83, 0xbfb8aa3b, v77
	v_exp_f32_e32 v82, v82
	v_exp_f32_e32 v83, v83
	v_pk_fma_f32 v[70:71], v[70:71], v[80:81], v[240:241] op_sel_hi:[1,0,1]
	v_pk_fma_f32 v[72:73], v[72:73], v[80:81], v[242:243] op_sel_hi:[1,0,1]
	v_add_f32_e32 v82, 1.0, v82
	v_add_f32_e32 v83, 1.0, v83
	v_rcp_f32_e32 v82, v82
	v_rcp_f32_e32 v83, v83
	v_pk_fma_f32 v[64:65], v[64:65], v[80:81], v[174:175] op_sel_hi:[1,0,1]
	v_pk_fma_f32 v[66:67], v[66:67], v[80:81], v[176:177] op_sel_hi:[1,0,1]
	v_pk_mul_f32 v[76:77], v[76:77], v[82:83]
	s_nop 0
	v_pk_mul_f32 v[68:69], v[68:69], v[76:77]
	v_pk_fma_f32 v[76:77], v[78:79], v[80:81], v[248:249] op_sel_hi:[1,0,1]
; __device__ __forceinline__ unsigned pk_bf16(float lo, float hi) { f32x2 v = {lo, hi}; bf16x2_t b = __builtin_convertvector(v, bf16x2_t); return __builtin_bit_cast(unsigned, b); }
;     __device__ __forceinline__ void operator()(const f32x4 (&acc)[2][2][4][2], const Unit& u, int wr, int wc, int fr, int fq) const {
;     ...
; #pragma unroll
;         for (int ai = 0; ai < 2; ++ai)
; #pragma unroll
;             for (int m = 0; m < 4; ++m) {
;                 float o[8]; const float rv = rsqrtf(rowss[row0 + ai * HALF + m * 16] * (1.0f / 1024.0f) + 1e-6f);
; #pragma unroll
;                 for (int n = 0; n < 2; ++n)
; #pragma unroll
;                     for (int j = 0; j < 4; ++j) { const float g = acc[ai][0][m][n][j] * rv + bz[0][n][j], up = acc[ai][1][m][n][j] * rv + bz[1][n][j];
;                         o[4 * n + j] = g * __builtin_amdgcn_rcpf(1.0f + __expf(-g)) * up; }
;                 u32x4 w; w.x = pk_bf16(o[0], o[1]); w.y = pk_bf16(o[2], o[3]); w.z = pk_bf16(o[4], o[5]); w.w = pk_bf16(o[6], o[7]);
;                 *(u32x4*)(act + (size_t)(row0 + ai * HALF + m * 16) * 2816 + col0) = w;
;             }
	s_nop 0
	v_mul_f32_e32 v78, 0xbfb8aa3b, v76
	v_mul_f32_e32 v79, 0xbfb8aa3b, v77
	v_exp_f32_e32 v78, v78
	v_exp_f32_e32 v79, v79
	v_add_f32_e32 v78, 1.0, v78
	v_add_f32_e32 v79, 1.0, v79
	v_rcp_f32_e32 v78, v78
	v_rcp_f32_e32 v79, v79
	s_nop 0
	v_pk_mul_f32 v[76:77], v[76:77], v[78:79]
	s_nop 0
	v_pk_mul_f32 v[70:71], v[70:71], v[76:77]
	v_mul_f32_e32 v76, 0xbfb8aa3b, v72
	v_mul_f32_e32 v77, 0xbfb8aa3b, v73
	v_exp_f32_e32 v76, v76
	v_exp_f32_e32 v77, v77
	v_add_f32_e32 v76, 1.0, v76
	v_add_f32_e32 v77, 1.0, v77
	v_rcp_f32_e32 v76, v76
	v_rcp_f32_e32 v77, v77
	s_nop 0
	v_pk_mul_f32 v[72:73], v[72:73], v[76:77]
	s_nop 0
	v_pk_mul_f32 v[72:73], v[64:65], v[72:73]
	v_pk_fma_f32 v[64:65], v[74:75], v[80:81], v[244:245] op_sel_hi:[1,0,1]
	s_nop 0
	v_mul_f32_e32 v74, 0xbfb8aa3b, v64
	v_mul_f32_e32 v75, 0xbfb8aa3b, v65
	v_exp_f32_e32 v74, v74
	v_exp_f32_e32 v75, v75
	v_add_f32_e32 v74, 1.0, v74
	v_add_f32_e32 v75, 1.0, v75
	v_rcp_f32_e32 v74, v74
	v_rcp_f32_e32 v75, v75
	s_nop 0
	v_pk_mul_f32 v[64:65], v[64:65], v[74:75]
	s_nop 0
	v_pk_mul_f32 v[74:75], v[66:67], v[64:65]
	v_cvt_pk_bf16_f32 v64, v68, v69
	s_mov_b32 s98, 0xb0000
	v_cvt_pk_bf16_f32 v65, v70, v71
	v_cvt_pk_bf16_f32 v66, v72, v73
	v_cvt_pk_bf16_f32 v67, v74, v75
	v_lshl_add_u64 v[68:69], v[194:195], 0, s[98:99]
	global_store_dwordx4 v[68:69], v[64:67], off
	s_nop 0
	s_nop 0
	v_fmamk_f32 v64, v167, 0x3a800000, v227
	s_nop 0
	v_rsq_f32_e32 v64, v64
	s_nop 0
	v_pk_fma_f32 v[60:61], v[60:61], v[64:65], v[246:247] op_sel_hi:[1,0,1]
	v_pk_fma_f32 v[52:53], v[52:53], v[64:65], v[238:239] op_sel_hi:[1,0,1]
	v_mul_f32_e32 v66, 0xbfb8aa3b, v60
	v_mul_f32_e32 v67, 0xbfb8aa3b, v61
	v_exp_f32_e32 v66, v66
	v_exp_f32_e32 v67, v67
	v_pk_fma_f32 v[54:55], v[54:55], v[64:65], v[240:241] op_sel_hi:[1,0,1]
	v_pk_fma_f32 v[56:57], v[56:57], v[64:65], v[242:243] op_sel_hi:[1,0,1]
	v_add_f32_e32 v66, 1.0, v66
	v_add_f32_e32 v67, 1.0, v67
	v_rcp_f32_e32 v66, v66
	v_rcp_f32_e32 v67, v67
	v_pk_fma_f32 v[48:49], v[48:49], v[64:65], v[174:175] op_sel_hi:[1,0,1]
	v_pk_fma_f32 v[50:51], v[50:51], v[64:65], v[176:177] op_sel_hi:[1,0,1]
	v_pk_mul_f32 v[60:61], v[60:61], v[66:67]
	s_nop 0
	v_pk_mul_f32 v[52:53], v[52:53], v[60:61]
	v_pk_fma_f32 v[60:61], v[62:63], v[64:65], v[248:249] op_sel_hi:[1,0,1]
	s_nop 0
	v_mul_f32_e32 v62, 0xbfb8aa3b, v60
	v_mul_f32_e32 v63, 0xbfb8aa3b, v61
	v_exp_f32_e32 v62, v62
	v_exp_f32_e32 v63, v63
	v_add_f32_e32 v62, 1.0, v62
	v_add_f32_e32 v63, 1.0, v63
	v_rcp_f32_e32 v62, v62
	v_rcp_f32_e32 v63, v63
	s_nop 0
	v_pk_mul_f32 v[60:61], v[60:61], v[62:63]
	s_nop 0
	v_pk_mul_f32 v[54:55], v[54:55], v[60:61]
	v_mul_f32_e32 v60, 0xbfb8aa3b, v56
	v_mul_f32_e32 v61, 0xbfb8aa3b, v57
	v_exp_f32_e32 v60, v60
	v_exp_f32_e32 v61, v61
	v_add_f32_e32 v60, 1.0, v60
	v_add_f32_e32 v61, 1.0, v61
	v_rcp_f32_e32 v60, v60
	v_rcp_f32_e32 v61, v61
	s_nop 0
	v_pk_mul_f32 v[56:57], v[56:57], v[60:61]
	s_nop 0
	v_pk_mul_f32 v[56:57], v[48:49], v[56:57]
	v_pk_fma_f32 v[48:49], v[58:59], v[64:65], v[244:245] op_sel_hi:[1,0,1]
	s_nop 0
	v_mul_f32_e32 v58, 0xbfb8aa3b, v48
	v_mul_f32_e32 v59, 0xbfb8aa3b, v49
	v_exp_f32_e32 v58, v58
	v_exp_f32_e32 v59, v59
	v_add_f32_e32 v58, 1.0, v58
	v_add_f32_e32 v59, 1.0, v59
	v_rcp_f32_e32 v58, v58
	v_rcp_f32_e32 v59, v59
	s_nop 0
	v_pk_mul_f32 v[48:49], v[48:49], v[58:59]
	s_nop 0
	v_pk_mul_f32 v[58:59], v[50:51], v[48:49]
	v_cvt_pk_bf16_f32 v48, v52, v53
	s_mov_b32 s98, 0xc6000
	v_cvt_pk_bf16_f32 v49, v54, v55
	v_cvt_pk_bf16_f32 v50, v56, v57
	v_cvt_pk_bf16_f32 v51, v58, v59
	v_lshl_add_u64 v[52:53], v[194:195], 0, s[98:99]
	global_store_dwordx4 v[52:53], v[48:51], off
	s_nop 0
	s_nop 0
	v_fmamk_f32 v48, v173, 0x3a800000, v227
	s_nop 0
	v_rsq_f32_e32 v48, v48
	s_nop 0
	v_pk_fma_f32 v[28:29], v[28:29], v[48:49], v[246:247] op_sel_hi:[1,0,1]
	v_pk_fma_f32 v[20:21], v[20:21], v[48:49], v[238:239] op_sel_hi:[1,0,1]
	v_mul_f32_e32 v50, 0xbfb8aa3b, v28
	v_mul_f32_e32 v51, 0xbfb8aa3b, v29
	v_exp_f32_e32 v50, v50
	v_exp_f32_e32 v51, v51
	v_pk_fma_f32 v[22:23], v[22:23], v[48:49], v[240:241] op_sel_hi:[1,0,1]
	v_pk_fma_f32 v[24:25], v[24:25], v[48:49], v[242:243] op_sel_hi:[1,0,1]
; __device__ __forceinline__ unsigned pk_bf16(float lo, float hi) { f32x2 v = {lo, hi}; bf16x2_t b = __builtin_convertvector(v, bf16x2_t); return __builtin_bit_cast(unsigned, b); }
; #define PG8_BAR __builtin_amdgcn_s_barrier()
;     __device__ __forceinline__ void operator()(const f32x4 (&acc)[2][2][4][2], const Unit& u, int wr, int wc, int fr, int fq) const {
;     ...
; #pragma unroll
;         for (int ai = 0; ai < 2; ++ai)
; #pragma unroll
;             for (int m = 0; m < 4; ++m) {
;                 float o[8]; const float rv = rsqrtf(rowss[row0 + ai * HALF + m * 16] * (1.0f / 1024.0f) + 1e-6f);
; #pragma unroll
;                 for (int n = 0; n < 2; ++n)
; #pragma unroll
;                     for (int j = 0; j < 4; ++j) { const float g = acc[ai][0][m][n][j] * rv + bz[0][n][j], up = acc[ai][1][m][n][j] * rv + bz[1][n][j];
;                         o[4 * n + j] = g * __builtin_amdgcn_rcpf(1.0f + __expf(-g)) * up; }
;                 u32x4 w; w.x = pk_bf16(o[0], o[1]); w.y = pk_bf16(o[2], o[3]); w.z = pk_bf16(o[4], o[5]); w.w = pk_bf16(o[6], o[7]);
;                 *(u32x4*)(act + (size_t)(row0 + ai * HALF + m * 16) * 2816 + col0) = w;
;             }
; template <class Epi, class Sched, bool ALIGN_EPI = false, bool SP2 = false, bool F16 = false>
; __device__ __forceinline__ void gemm_phase(PG8_LAS unsigned char* lds, const Gemm g, const Sched& S, const Epi& E) {
;     ...
;         if (!has_next) break;
; #pragma unroll
;         for (int a = 0; a < 2; ++a)
; #pragma unroll
;             for (int b = 0; b < 2; ++b)
; #pragma unroll
;                 for (int m = 0; m < 4; ++m)
; #pragma unroll
;                     for (int n = 0; n < 2; ++n) acc[a][b][m][n] = (f32x4){0.f, 0.f, 0.f, 0.f};
;         cur = nxt; cA = nA; cB = nB; ++ui;
;         if constexpr (ALIGN_EPI) { if (wr == 1) PG8_BAR; }
	v_add_f32_e32 v50, 1.0, v50
	v_add_f32_e32 v51, 1.0, v51
	v_rcp_f32_e32 v50, v50
	v_rcp_f32_e32 v51, v51
	v_pk_fma_f32 v[16:17], v[16:17], v[48:49], v[174:175] op_sel_hi:[1,0,1]
	v_pk_fma_f32 v[18:19], v[18:19], v[48:49], v[176:177] op_sel_hi:[1,0,1]
	v_pk_mul_f32 v[28:29], v[28:29], v[50:51]
	s_nop 0
	v_pk_mul_f32 v[20:21], v[20:21], v[28:29]
	v_pk_fma_f32 v[28:29], v[30:31], v[48:49], v[248:249] op_sel_hi:[1,0,1]
	s_nop 0
	v_mul_f32_e32 v30, 0xbfb8aa3b, v28
	v_mul_f32_e32 v31, 0xbfb8aa3b, v29
	v_exp_f32_e32 v30, v30
	v_exp_f32_e32 v31, v31
	v_add_f32_e32 v30, 1.0, v30
	v_add_f32_e32 v31, 1.0, v31
	v_rcp_f32_e32 v30, v30
	v_rcp_f32_e32 v31, v31
	s_nop 0
	v_pk_mul_f32 v[28:29], v[28:29], v[30:31]
	s_nop 0
	v_pk_mul_f32 v[22:23], v[22:23], v[28:29]
	v_mul_f32_e32 v28, 0xbfb8aa3b, v24
	v_mul_f32_e32 v29, 0xbfb8aa3b, v25
	v_exp_f32_e32 v28, v28
	v_exp_f32_e32 v29, v29
	v_add_f32_e32 v28, 1.0, v28
	v_add_f32_e32 v29, 1.0, v29
	v_rcp_f32_e32 v28, v28
	v_rcp_f32_e32 v29, v29
	s_nop 0
	v_pk_mul_f32 v[24:25], v[24:25], v[28:29]
	s_nop 0
	v_pk_mul_f32 v[24:25], v[16:17], v[24:25]
	v_pk_fma_f32 v[16:17], v[26:27], v[48:49], v[244:245] op_sel_hi:[1,0,1]
	s_nop 0
	v_mul_f32_e32 v26, 0xbfb8aa3b, v16
	v_mul_f32_e32 v27, 0xbfb8aa3b, v17
	v_exp_f32_e32 v26, v26
	v_exp_f32_e32 v27, v27
	v_add_f32_e32 v26, 1.0, v26
	v_add_f32_e32 v27, 1.0, v27
	v_rcp_f32_e32 v26, v26
	v_rcp_f32_e32 v27, v27
	s_nop 0
	v_pk_mul_f32 v[16:17], v[16:17], v[26:27]
	s_nop 0
	v_pk_mul_f32 v[26:27], v[18:19], v[16:17]
	v_cvt_pk_bf16_f32 v16, v20, v21
	s_mov_b32 s98, 0xdc000
	v_cvt_pk_bf16_f32 v17, v22, v23
	v_cvt_pk_bf16_f32 v18, v24, v25
	v_cvt_pk_bf16_f32 v19, v26, v27
	v_lshl_add_u64 v[20:21], v[194:195], 0, s[98:99]
	global_store_dwordx4 v[20:21], v[16:19], off
	s_nop 0
	s_nop 0
	v_fmamk_f32 v16, v250, 0x3a800000, v227
	s_nop 0
	v_rsq_f32_e32 v16, v16
	s_nop 0
	v_pk_fma_f32 v[12:13], v[12:13], v[16:17], v[246:247] op_sel_hi:[1,0,1]
	v_pk_fma_f32 v[4:5], v[4:5], v[16:17], v[238:239] op_sel_hi:[1,0,1]
	v_mul_f32_e32 v18, 0xbfb8aa3b, v12
	v_mul_f32_e32 v19, 0xbfb8aa3b, v13
	v_exp_f32_e32 v18, v18
	v_exp_f32_e32 v19, v19
	v_pk_fma_f32 v[6:7], v[6:7], v[16:17], v[240:241] op_sel_hi:[1,0,1]
	v_pk_fma_f32 v[8:9], v[8:9], v[16:17], v[242:243] op_sel_hi:[1,0,1]
	v_add_f32_e32 v18, 1.0, v18
	v_add_f32_e32 v19, 1.0, v19
	v_rcp_f32_e32 v18, v18
	v_rcp_f32_e32 v19, v19
	v_pk_fma_f32 v[0:1], v[0:1], v[16:17], v[174:175] op_sel_hi:[1,0,1]
	v_pk_fma_f32 v[2:3], v[2:3], v[16:17], v[176:177] op_sel_hi:[1,0,1]
	s_andn2_b64 vcc, exec, s[40:41]
	v_pk_mul_f32 v[12:13], v[12:13], v[18:19]
	s_nop 0
	v_pk_mul_f32 v[4:5], v[4:5], v[12:13]
	v_pk_fma_f32 v[12:13], v[14:15], v[16:17], v[248:249] op_sel_hi:[1,0,1]
	s_nop 0
	v_mul_f32_e32 v14, 0xbfb8aa3b, v12
	v_mul_f32_e32 v15, 0xbfb8aa3b, v13
	v_exp_f32_e32 v14, v14
	v_exp_f32_e32 v15, v15
	v_add_f32_e32 v14, 1.0, v14
	v_add_f32_e32 v15, 1.0, v15
	v_rcp_f32_e32 v14, v14
	v_rcp_f32_e32 v15, v15
	s_nop 0
	v_pk_mul_f32 v[12:13], v[12:13], v[14:15]
	s_nop 0
	v_pk_mul_f32 v[6:7], v[6:7], v[12:13]
	v_mul_f32_e32 v12, 0xbfb8aa3b, v8
	v_mul_f32_e32 v13, 0xbfb8aa3b, v9
	v_exp_f32_e32 v12, v12
	v_exp_f32_e32 v13, v13
	v_add_f32_e32 v12, 1.0, v12
	v_add_f32_e32 v13, 1.0, v13
	v_rcp_f32_e32 v12, v12
	v_rcp_f32_e32 v13, v13
	s_nop 0
	v_pk_mul_f32 v[8:9], v[8:9], v[12:13]
	s_nop 0
	v_pk_mul_f32 v[8:9], v[0:1], v[8:9]
	v_pk_fma_f32 v[0:1], v[10:11], v[16:17], v[244:245] op_sel_hi:[1,0,1]
	s_nop 0
	v_mul_f32_e32 v10, 0xbfb8aa3b, v0
	v_mul_f32_e32 v11, 0xbfb8aa3b, v1
	v_exp_f32_e32 v10, v10
	v_exp_f32_e32 v11, v11
	v_add_f32_e32 v10, 1.0, v10
	v_add_f32_e32 v11, 1.0, v11
	v_rcp_f32_e32 v10, v10
	v_rcp_f32_e32 v11, v11
	s_nop 0
	v_pk_mul_f32 v[0:1], v[0:1], v[10:11]
	s_nop 0
	v_pk_mul_f32 v[10:11], v[2:3], v[0:1]
	v_cvt_pk_bf16_f32 v0, v4, v5
	s_mov_b32 s98, 0xf2000
	v_cvt_pk_bf16_f32 v1, v6, v7
	v_cvt_pk_bf16_f32 v2, v8, v9
	v_cvt_pk_bf16_f32 v3, v10, v11
	v_lshl_add_u64 v[4:5], v[194:195], 0, s[98:99]
	global_store_dwordx4 v[4:5], v[0:3], off
	s_cbranch_vccnz .LBB0_900
	s_andn2_b64 vcc, exec, s[0:1]
	s_cbranch_vccnz .LBB0_899
	s_barrier
	s_branch .LBB0_899
